# adds: next-tile row-rstd loads of the gate-up and in-proj GEMM epilogues are waited at the end of the epilogue instead of right after issue
# baseline (speedup 1.0000x reference)
.LBB0_614:
	s_and_b64 s[22:23], s[4:5], s[12:13]
	v_mov_b32_e32 v148, 0
	s_and_saveexec_b64 s[20:21], s[22:23]
	s_cbranch_execz .LBB0_616
	v_add_u32_e32 v138, s18, v142
	v_ashrrev_i32_e32 v139, 31, v138
	v_readlane_b32 s18, v253, 50
	v_lshlrev_b64 v[138:139], 6, v[138:139]
	v_readlane_b32 s19, v253, 51
	s_nop 1
	v_lshl_add_u64 v[156:157], s[18:19], 0, v[138:139]
	global_load_dwordx4 v[160:163], v[156:157], off offset:32
	global_load_dwordx4 v[164:167], v[156:157], off offset:16
	global_load_dwordx4 v[168:171], v[156:157], off
	global_load_dwordx4 v[172:175], v[156:157], off offset:48
.LBB0_616:
	s_or_b64 exec, exec, s[20:21]
	v_lshl_add_u32 v138, s36, 10, v146
	ds_read2_b32 v[150:151], v138 offset1:16
	ds_read2_b32 v[152:153], v138 offset0:32 offset1:48
	ds_read2_b32 v[140:141], v138 offset0:128 offset1:144
	ds_read2_b32 v[138:139], v138 offset0:160 offset1:176
	v_readlane_b32 s20, v254, 1
	s_lshl_b32 s18, s41, 8
	s_waitcnt lgkmcnt(0)
	v_pk_mul_f32 v[126:127], v[126:127], v[150:151] op_sel_hi:[1,0]
	v_pk_mul_f32 v[122:123], v[122:123], v[150:151] op_sel_hi:[1,0]
	v_readlane_b32 s21, v254, 2
	v_lshl_add_u32 v149, s40, 8, v143
	s_ashr_i32 s19, s18, 31
	v_pk_mul_f32 v[128:129], v[128:129], v[150:151] op_sel_hi:[1,0]
	v_pk_mul_f32 v[154:155], v[124:125], v[150:151] op_sel_hi:[1,0]
	v_cvt_pk_bf16_f32 v124, v126, v127
	v_cvt_pk_bf16_f32 v126, v122, v123
	v_mov_b64_e32 v[122:123], s[20:21]
	s_movk_i32 s22, 0x1400
	v_cvt_pk_bf16_f32 v125, v128, v129
	v_mad_i64_i32 v[128:129], s[20:21], v149, s22, v[122:123]
	s_lshl_b64 s[18:19], s[18:19], 1
	v_lshl_add_u64 v[128:129], v[128:129], 0, s[18:19]
	v_lshl_add_u64 v[128:129], v[128:129], 0, s[2:3]
	v_lshl_add_u64 v[128:129], v[128:129], 0, v[0:1]
	v_cvt_pk_bf16_f32 v127, v154, v155
	global_store_dwordx4 v[128:129], v[124:127], off
	v_pk_mul_f32 v[120:121], v[120:121], v[150:151] op_sel_hi:[1,0]
	v_pk_mul_f32 v[118:119], v[118:119], v[150:151] op_sel_hi:[1,0]
	v_pk_mul_f32 v[124:125], v[112:113], v[150:151] op_sel_hi:[1,0]
	v_pk_mul_f32 v[112:113], v[110:111], v[150:151] op_sel_hi:[1,0]
	v_cvt_pk_bf16_f32 v110, v118, v119
	v_cvt_pk_bf16_f32 v111, v120, v121
	v_pk_mul_f32 v[88:89], v[88:89], v[152:153] op_sel_hi:[1,0]
	v_cvt_pk_bf16_f32 v112, v112, v113
	v_cvt_pk_bf16_f32 v113, v124, v125
	global_store_dwordx4 v[128:129], v[110:113], off offset:256
	v_pk_mul_f32 v[86:87], v[86:87], v[152:153] op_sel_hi:[1,0]
	v_pk_mul_f32 v[62:63], v[62:63], v[140:141] op_sel_hi:[1,0]
	v_or_b32_e32 v111, 16, v149
	v_mov_b32_e32 v110, v151
	v_pk_mul_f32 v[112:113], v[116:117], v[110:111] op_sel_hi:[1,0]
	v_pk_mul_f32 v[116:117], v[108:109], v[110:111] op_sel_hi:[1,0]
	v_pk_mul_f32 v[108:109], v[106:107], v[110:111] op_sel_hi:[1,0]
	v_cvt_pk_bf16_f32 v107, v112, v113
	v_mad_i64_i32 v[112:113], s[20:21], v111, s22, v[122:123]
	v_lshl_add_u64 v[112:113], v[112:113], 0, s[18:19]
	v_lshl_add_u64 v[112:113], v[112:113], 0, s[2:3]
	v_pk_mul_f32 v[114:115], v[114:115], v[110:111] op_sel_hi:[1,0]
	v_lshl_add_u64 v[112:113], v[112:113], 0, v[0:1]
	v_cvt_pk_bf16_f32 v106, v114, v115
	v_cvt_pk_bf16_f32 v108, v108, v109
	v_cvt_pk_bf16_f32 v109, v116, v117
	global_store_dwordx4 v[112:113], v[106:109], off
	v_pk_mul_f32 v[104:105], v[104:105], v[110:111] op_sel_hi:[1,0]
	v_pk_mul_f32 v[102:103], v[102:103], v[110:111] op_sel_hi:[1,0]
	v_pk_mul_f32 v[106:107], v[96:97], v[110:111] op_sel_hi:[1,0]
	v_pk_mul_f32 v[96:97], v[94:95], v[110:111] op_sel_hi:[1,0]
	v_cvt_pk_bf16_f32 v94, v102, v103
	v_cvt_pk_bf16_f32 v95, v104, v105
	v_or_b32_e32 v102, 32, v149
	v_cvt_pk_bf16_f32 v96, v96, v97
	v_cvt_pk_bf16_f32 v97, v106, v107
	global_store_dwordx4 v[112:113], v[94:97], off offset:256
	v_pk_mul_f32 v[64:65], v[64:65], v[140:141] op_sel_hi:[1,0]
	v_pk_mul_f32 v[56:57], v[56:57], v[140:141] op_sel_hi:[1,0]
	v_pk_mul_f32 v[94:95], v[100:101], v[152:153] op_sel_hi:[1,0]
	v_pk_mul_f32 v[96:97], v[98:99], v[152:153] op_sel_hi:[1,0]
	v_pk_mul_f32 v[98:99], v[92:93], v[152:153] op_sel_hi:[1,0]
	v_pk_mul_f32 v[92:93], v[90:91], v[152:153] op_sel_hi:[1,0]
	v_cvt_pk_bf16_f32 v91, v94, v95
	v_mad_i64_i32 v[94:95], s[20:21], v102, s22, v[122:123]
	v_lshl_add_u64 v[94:95], v[94:95], 0, s[18:19]
	v_lshl_add_u64 v[94:95], v[94:95], 0, s[2:3]
	v_cvt_pk_bf16_f32 v90, v96, v97
	v_lshl_add_u64 v[94:95], v[94:95], 0, v[0:1]
	v_cvt_pk_bf16_f32 v92, v92, v93
	v_cvt_pk_bf16_f32 v93, v98, v99
	global_store_dwordx4 v[94:95], v[90:93], off
	v_pk_mul_f32 v[54:55], v[54:55], v[140:141] op_sel_hi:[1,0]
	v_pk_mul_f32 v[24:25], v[24:25], v[138:139] op_sel_hi:[1,0]
	v_pk_mul_f32 v[90:91], v[80:81], v[152:153] op_sel_hi:[1,0]
	v_pk_mul_f32 v[80:81], v[78:79], v[152:153] op_sel_hi:[1,0]
	v_cvt_pk_bf16_f32 v78, v86, v87
	v_cvt_pk_bf16_f32 v79, v88, v89
	v_pk_mul_f32 v[22:23], v[22:23], v[138:139] op_sel_hi:[1,0]
	v_cvt_pk_bf16_f32 v80, v80, v81
	v_cvt_pk_bf16_f32 v81, v90, v91
	global_store_dwordx4 v[94:95], v[78:81], off offset:256
	s_nop 1
	v_or_b32_e32 v79, 48, v149
	v_mov_b32_e32 v78, v153
	v_pk_mul_f32 v[80:81], v[84:85], v[78:79] op_sel_hi:[1,0]
	v_pk_mul_f32 v[84:85], v[76:77], v[78:79] op_sel_hi:[1,0]
	v_pk_mul_f32 v[76:77], v[74:75], v[78:79] op_sel_hi:[1,0]
	v_cvt_pk_bf16_f32 v75, v80, v81
	v_mad_i64_i32 v[80:81], s[20:21], v79, s22, v[122:123]
	v_lshl_add_u64 v[80:81], v[80:81], 0, s[18:19]
	v_lshl_add_u64 v[80:81], v[80:81], 0, s[2:3]
	v_pk_mul_f32 v[82:83], v[82:83], v[78:79] op_sel_hi:[1,0]
	v_lshl_add_u64 v[80:81], v[80:81], 0, v[0:1]
	v_cvt_pk_bf16_f32 v74, v82, v83
	v_cvt_pk_bf16_f32 v76, v76, v77
	v_cvt_pk_bf16_f32 v77, v84, v85
	global_store_dwordx4 v[80:81], v[74:77], off
	v_pk_mul_f32 v[72:73], v[72:73], v[78:79] op_sel_hi:[1,0]
	v_pk_mul_f32 v[70:71], v[70:71], v[78:79] op_sel_hi:[1,0]
	v_pk_mul_f32 v[74:75], v[68:69], v[78:79] op_sel_hi:[1,0]
	v_pk_mul_f32 v[68:69], v[66:67], v[78:79] op_sel_hi:[1,0]
	v_cvt_pk_bf16_f32 v66, v70, v71
	v_cvt_pk_bf16_f32 v67, v72, v73
	s_nop 0
	v_cvt_pk_bf16_f32 v68, v68, v69
	v_cvt_pk_bf16_f32 v69, v74, v75
	global_store_dwordx4 v[80:81], v[66:69], off offset:256
	s_nop 1
	v_add_u32_e32 v68, 0x80, v149
	v_pk_mul_f32 v[66:67], v[60:61], v[140:141] op_sel_hi:[1,0]
	v_pk_mul_f32 v[60:61], v[58:59], v[140:141] op_sel_hi:[1,0]
	v_cvt_pk_bf16_f32 v58, v62, v63
	v_mad_i64_i32 v[62:63], s[20:21], v68, s22, v[122:123]
	v_lshl_add_u64 v[62:63], v[62:63], 0, s[18:19]
	v_lshl_add_u64 v[62:63], v[62:63], 0, s[2:3]
	v_cvt_pk_bf16_f32 v59, v64, v65
	v_lshl_add_u64 v[62:63], v[62:63], 0, v[0:1]
	v_cvt_pk_bf16_f32 v60, v60, v61
	v_cvt_pk_bf16_f32 v61, v66, v67
	global_store_dwordx4 v[62:63], v[58:61], off
	s_nop 1
	v_pk_mul_f32 v[58:59], v[48:49], v[140:141] op_sel_hi:[1,0]
	v_pk_mul_f32 v[48:49], v[46:47], v[140:141] op_sel_hi:[1,0]
	v_cvt_pk_bf16_f32 v46, v54, v55
	v_cvt_pk_bf16_f32 v47, v56, v57
	s_nop 0
	v_cvt_pk_bf16_f32 v48, v48, v49
	v_cvt_pk_bf16_f32 v49, v58, v59
	global_store_dwordx4 v[62:63], v[46:49], off offset:256
	s_nop 1
	v_add_u32_e32 v47, 0x90, v149
	v_mov_b32_e32 v46, v141
	v_pk_mul_f32 v[48:49], v[52:53], v[46:47] op_sel_hi:[1,0]
	v_pk_mul_f32 v[52:53], v[44:45], v[46:47] op_sel_hi:[1,0]
	v_pk_mul_f32 v[44:45], v[42:43], v[46:47] op_sel_hi:[1,0]
	v_cvt_pk_bf16_f32 v43, v48, v49
	v_mad_i64_i32 v[48:49], s[20:21], v47, s22, v[122:123]
	v_lshl_add_u64 v[48:49], v[48:49], 0, s[18:19]
	v_lshl_add_u64 v[48:49], v[48:49], 0, s[2:3]
	v_pk_mul_f32 v[50:51], v[50:51], v[46:47] op_sel_hi:[1,0]
	v_lshl_add_u64 v[48:49], v[48:49], 0, v[0:1]
	v_cvt_pk_bf16_f32 v42, v50, v51
	v_cvt_pk_bf16_f32 v44, v44, v45
	v_cvt_pk_bf16_f32 v45, v52, v53
	global_store_dwordx4 v[48:49], v[42:45], off
	v_pk_mul_f32 v[40:41], v[40:41], v[46:47] op_sel_hi:[1,0]
	v_pk_mul_f32 v[38:39], v[38:39], v[46:47] op_sel_hi:[1,0]
	v_pk_mul_f32 v[42:43], v[32:33], v[46:47] op_sel_hi:[1,0]
	v_pk_mul_f32 v[32:33], v[30:31], v[46:47] op_sel_hi:[1,0]
	v_cvt_pk_bf16_f32 v30, v38, v39
	v_cvt_pk_bf16_f32 v31, v40, v41
	v_add_u32_e32 v38, 0xa0, v149
	v_cvt_pk_bf16_f32 v32, v32, v33
	v_cvt_pk_bf16_f32 v33, v42, v43
	global_store_dwordx4 v[48:49], v[30:33], off offset:256
	s_nop 1
	v_pk_mul_f32 v[30:31], v[36:37], v[138:139] op_sel_hi:[1,0]
	v_pk_mul_f32 v[32:33], v[34:35], v[138:139] op_sel_hi:[1,0]
	v_pk_mul_f32 v[34:35], v[28:29], v[138:139] op_sel_hi:[1,0]
	v_pk_mul_f32 v[28:29], v[26:27], v[138:139] op_sel_hi:[1,0]
	v_cvt_pk_bf16_f32 v27, v30, v31
	v_mad_i64_i32 v[30:31], s[20:21], v38, s22, v[122:123]
	v_lshl_add_u64 v[30:31], v[30:31], 0, s[18:19]
	v_lshl_add_u64 v[30:31], v[30:31], 0, s[2:3]
	v_cvt_pk_bf16_f32 v26, v32, v33
	v_lshl_add_u64 v[30:31], v[30:31], 0, v[0:1]
	v_cvt_pk_bf16_f32 v28, v28, v29
	v_cvt_pk_bf16_f32 v29, v34, v35
	global_store_dwordx4 v[30:31], v[26:29], off
	s_nop 1
	v_pk_mul_f32 v[26:27], v[16:17], v[138:139] op_sel_hi:[1,0]
	v_pk_mul_f32 v[16:17], v[14:15], v[138:139] op_sel_hi:[1,0]
	v_cvt_pk_bf16_f32 v14, v22, v23
	v_cvt_pk_bf16_f32 v15, v24, v25
	s_nop 0
	v_cvt_pk_bf16_f32 v16, v16, v17
	v_cvt_pk_bf16_f32 v17, v26, v27
	global_store_dwordx4 v[30:31], v[14:17], off offset:256
	s_nop 1
	v_add_u32_e32 v15, 0xb0, v149
	v_mov_b32_e32 v14, v139
	v_pk_mul_f32 v[16:17], v[20:21], v[14:15] op_sel_hi:[1,0]
	v_pk_mul_f32 v[20:21], v[12:13], v[14:15] op_sel_hi:[1,0]
	v_pk_mul_f32 v[12:13], v[10:11], v[14:15] op_sel_hi:[1,0]
	v_cvt_pk_bf16_f32 v11, v16, v17
	v_mad_i64_i32 v[16:17], s[20:21], v15, s22, v[122:123]
	v_lshl_add_u64 v[16:17], v[16:17], 0, s[18:19]
	v_lshl_add_u64 v[16:17], v[16:17], 0, s[2:3]
	v_pk_mul_f32 v[18:19], v[18:19], v[14:15] op_sel_hi:[1,0]
	v_lshl_add_u64 v[16:17], v[16:17], 0, v[0:1]
	v_cvt_pk_bf16_f32 v10, v18, v19
	v_cvt_pk_bf16_f32 v12, v12, v13
	v_cvt_pk_bf16_f32 v13, v20, v21
	global_store_dwordx4 v[16:17], v[10:13], off
	v_pk_mul_f32 v[8:9], v[8:9], v[14:15] op_sel_hi:[1,0]
	v_pk_mul_f32 v[6:7], v[6:7], v[14:15] op_sel_hi:[1,0]
	v_pk_mul_f32 v[10:11], v[4:5], v[14:15] op_sel_hi:[1,0]
	v_pk_mul_f32 v[4:5], v[2:3], v[14:15] op_sel_hi:[1,0]
	v_cvt_pk_bf16_f32 v2, v6, v7
	v_cvt_pk_bf16_f32 v3, v8, v9
	s_nop 0
	v_cvt_pk_bf16_f32 v4, v4, v5
	v_cvt_pk_bf16_f32 v5, v10, v11
	global_store_dwordx4 v[16:17], v[2:5], off offset:256
	s_andn2_b64 vcc, exec, s[12:13]
	s_mov_b64 s[12:13], -1
	s_cbranch_vccnz .LBB0_607
	s_and_saveexec_b64 s[12:13], s[4:5]
	s_waitcnt vmcnt(16)
	v_add_f32_e32 v138, v168, v169
	v_add_f32_e32 v139, v170, v171
	v_add_f32_e32 v138, v138, v139
	v_add_f32_e32 v139, v164, v165
	v_add_f32_e32 v140, v166, v167
	v_add_f32_e32 v139, v139, v140
	v_add_f32_e32 v138, v138, v139
	v_add_f32_e32 v139, v160, v161
	v_add_f32_e32 v140, v162, v163
	v_add_f32_e32 v139, v139, v140
	v_add_f32_e32 v138, v138, v139
	v_add_f32_e32 v139, v172, v173
	v_add_f32_e32 v140, v174, v175
	v_add_f32_e32 v139, v139, v140
	v_add_f32_e32 v138, v138, v139
	s_mov_b32 s18, 0x800000
	v_fmamk_f32 v138, v138, 0x3a800000, v241
	v_mul_f32_e32 v139, 0x4b800000, v138
	v_cmp_gt_f32_e32 vcc, s18, v138
	s_nop 1
	v_cndmask_b32_e32 v138, v138, v139, vcc
	v_rsq_f32_e32 v138, v138
	s_nop 0
	v_mul_f32_e32 v139, 0x45800000, v138
	v_cndmask_b32_e32 v148, v138, v139, vcc
	s_lshl_b32 s18, s36, 8
	s_xor_b32 s18, s18, 0x100
	v_lshl_add_u32 v2, s18, 2, v145
	ds_write_b32 v2, v148
	s_or_b64 exec, exec, s[12:13]
	s_andn2_b64 vcc, exec, s[8:9]
	s_cbranch_vccnz .LBB0_606
	s_barrier
	s_branch .LBB0_606
	s_nop 0
	s_nop 0
	s_nop 0

.LBB0_691:
	s_and_b64 s[20:21], s[40:41], s[10:11]
	v_mov_b32_e32 v153, 0
	s_and_saveexec_b64 s[18:19], s[20:21]
	s_cbranch_execz .LBB0_693
	v_add_u32_e32 v136, s16, v146
	v_ashrrev_i32_e32 v137, 31, v136
	v_readlane_b32 s16, v253, 50
	v_lshlrev_b64 v[136:137], 6, v[136:137]
	v_readlane_b32 s17, v253, 51
	s_nop 1
	v_lshl_add_u64 v[144:145], s[16:17], 0, v[136:137]
	global_load_dwordx4 v[160:163], v[144:145], off offset:32
	global_load_dwordx4 v[164:167], v[144:145], off offset:16
	global_load_dwordx4 v[168:171], v[144:145], off
	global_load_dwordx4 v[172:175], v[144:145], off offset:48
.LBB0_693:
	s_or_b64 exec, exec, s[18:19]
	v_lshl_add_u32 v136, s33, 10, v150
	ds_read2_b32 v[142:143], v136 offset1:16
	ds_read2_b32 v[140:141], v136 offset0:32 offset1:48
	ds_read2_b32 v[138:139], v136 offset0:128 offset1:144
	ds_read2_b32 v[136:137], v136 offset0:160 offset1:176
	v_readlane_b32 s16, v254, 1
	s_waitcnt lgkmcnt(0)
	v_pk_mul_f32 v[126:127], v[126:127], v[142:143] op_sel_hi:[1,0]
	v_pk_mul_f32 v[128:129], v[128:129], v[142:143] op_sel_hi:[1,0]
	v_pk_mul_f32 v[120:121], v[120:121], v[142:143] op_sel_hi:[1,0]
	v_pk_mul_f32 v[118:119], v[118:119], v[142:143] op_sel_hi:[1,0]
	v_pk_mul_f32 v[124:125], v[124:125], v[142:143] op_sel_hi:[1,0]
	v_pk_mul_f32 v[122:123], v[122:123], v[142:143] op_sel_hi:[1,0]
	v_pk_mul_f32 v[116:117], v[116:117], v[142:143] op_sel_hi:[1,0]
	v_pk_mul_f32 v[114:115], v[114:115], v[142:143] op_sel_hi:[1,0]
	v_mul_f32_e32 v142, 0xbfb8aa3b, v126
	v_exp_f32_e32 v142, v142
	v_lshl_or_b32 v144, s38, 7, v151
	v_readlane_b32 s17, v254, 2
	v_lshl_add_u32 v154, s37, 8, v147
	v_add_f32_e32 v142, 1.0, v142
	v_rcp_f32_e32 v142, v142
	v_ashrrev_i32_e32 v145, 31, v144
	s_movk_i32 s18, 0x1600
	v_pk_mul_f32 v[94:95], v[94:95], v[140:141] op_sel_hi:[1,0]
	v_mul_f32_e32 v126, v126, v142
	v_mul_f32_e32 v118, v118, v126
	v_mul_f32_e32 v126, 0xbfb8aa3b, v127
	v_exp_f32_e32 v126, v126
	v_pk_mul_f32 v[86:87], v[86:87], v[140:141] op_sel_hi:[1,0]
	v_pk_mul_f32 v[96:97], v[96:97], v[140:141] op_sel_hi:[1,0]
	v_pk_mul_f32 v[88:89], v[88:89], v[140:141] op_sel_hi:[1,0]
	v_add_f32_e32 v126, 1.0, v126
	v_rcp_f32_e32 v126, v126
	v_pk_mul_f32 v[90:91], v[90:91], v[140:141] op_sel_hi:[1,0]
	v_pk_mul_f32 v[92:93], v[92:93], v[140:141] op_sel_hi:[1,0]
	v_pk_mul_f32 v[62:63], v[62:63], v[138:139] op_sel_hi:[1,0]
	v_mul_f32_e32 v126, v127, v126
	v_mul_f32_e32 v119, v119, v126
	v_cvt_pk_bf16_f32 v118, v118, v119
	v_mul_f32_e32 v119, 0xbfb8aa3b, v128
	v_exp_f32_e32 v119, v119
	v_pk_mul_f32 v[54:55], v[54:55], v[138:139] op_sel_hi:[1,0]
	v_pk_mul_f32 v[64:65], v[64:65], v[138:139] op_sel_hi:[1,0]
	v_pk_mul_f32 v[56:57], v[56:57], v[138:139] op_sel_hi:[1,0]
	v_add_f32_e32 v119, 1.0, v119
	v_rcp_f32_e32 v119, v119
	v_pk_mul_f32 v[58:59], v[58:59], v[138:139] op_sel_hi:[1,0]
	v_pk_mul_f32 v[60:61], v[60:61], v[138:139] op_sel_hi:[1,0]
	v_pk_mul_f32 v[30:31], v[30:31], v[136:137] op_sel_hi:[1,0]
	v_mul_f32_e32 v119, v128, v119
	v_mul_f32_e32 v119, v120, v119
	v_mul_f32_e32 v120, 0xbfb8aa3b, v129
	v_exp_f32_e32 v120, v120
	v_pk_mul_f32 v[22:23], v[22:23], v[136:137] op_sel_hi:[1,0]
	v_pk_mul_f32 v[32:33], v[32:33], v[136:137] op_sel_hi:[1,0]
	v_pk_mul_f32 v[24:25], v[24:25], v[136:137] op_sel_hi:[1,0]
	v_add_f32_e32 v120, 1.0, v120
	v_rcp_f32_e32 v120, v120
	v_pk_mul_f32 v[26:27], v[26:27], v[136:137] op_sel_hi:[1,0]
	v_pk_mul_f32 v[28:29], v[28:29], v[136:137] op_sel_hi:[1,0]
	v_mul_f32_e32 v120, v129, v120
	v_mul_f32_e32 v120, v121, v120
	v_cvt_pk_bf16_f32 v119, v119, v120
	v_mul_f32_e32 v120, 0xbfb8aa3b, v122
	v_exp_f32_e32 v120, v120
	s_nop 0
	v_add_f32_e32 v120, 1.0, v120
	v_rcp_f32_e32 v120, v120
	s_nop 0
	v_mul_f32_e32 v120, v122, v120
	v_mul_f32_e32 v114, v114, v120
	v_mul_f32_e32 v120, 0xbfb8aa3b, v123
	v_exp_f32_e32 v120, v120
	s_nop 0
	v_add_f32_e32 v120, 1.0, v120
	v_rcp_f32_e32 v120, v120
	s_nop 0
	v_mul_f32_e32 v120, v123, v120
	v_mul_f32_e32 v115, v115, v120
	v_cvt_pk_bf16_f32 v120, v114, v115
	v_mul_f32_e32 v114, 0xbfb8aa3b, v124
	v_mul_f32_e32 v115, 0xbfb8aa3b, v125
	v_exp_f32_e32 v114, v114
	v_exp_f32_e32 v115, v115
	v_add_f32_e32 v114, 1.0, v114
	v_add_f32_e32 v115, 1.0, v115
	v_rcp_f32_e32 v114, v114
	v_rcp_f32_e32 v115, v115
	v_mul_f32_e32 v114, v124, v114
	v_mul_f32_e32 v115, v125, v115
	v_mul_f32_e32 v114, v116, v114
	v_mul_f32_e32 v115, v117, v115
	v_cvt_pk_bf16_f32 v121, v114, v115
	v_mov_b64_e32 v[114:115], s[16:17]
	v_mad_i64_i32 v[122:123], s[16:17], v154, s18, v[114:115]
	v_lshlrev_b64 v[116:117], 1, v[144:145]
	v_lshl_add_u64 v[122:123], v[122:123], 0, v[116:117]
	global_store_dwordx4 v[122:123], v[118:121], off
	s_nop 1
	v_or_b32_e32 v119, 16, v154
	v_mov_b32_e32 v118, v143
	v_pk_mul_f32 v[110:111], v[110:111], v[118:119] op_sel_hi:[1,0]
	v_pk_mul_f32 v[120:121], v[100:101], v[118:119] op_sel_hi:[1,0]
	v_pk_mul_f32 v[100:101], v[98:99], v[118:119] op_sel_hi:[1,0]
	v_mul_f32_e32 v98, 0xbfb8aa3b, v110
	v_mul_f32_e32 v99, 0xbfb8aa3b, v111
	v_exp_f32_e32 v98, v98
	v_exp_f32_e32 v99, v99
	v_pk_mul_f32 v[102:103], v[102:103], v[118:119] op_sel_hi:[1,0]
	v_pk_mul_f32 v[112:113], v[112:113], v[118:119] op_sel_hi:[1,0]
	v_add_f32_e32 v98, 1.0, v98
	v_add_f32_e32 v99, 1.0, v99
	v_rcp_f32_e32 v98, v98
	v_rcp_f32_e32 v99, v99
	v_pk_mul_f32 v[104:105], v[104:105], v[118:119] op_sel_hi:[1,0]
	v_pk_mul_f32 v[106:107], v[106:107], v[118:119] op_sel_hi:[1,0]
	v_mul_f32_e32 v98, v110, v98
	v_mul_f32_e32 v99, v111, v99
	v_mul_f32_e32 v98, v102, v98
	v_mul_f32_e32 v99, v103, v99
	v_cvt_pk_bf16_f32 v98, v98, v99
	v_mul_f32_e32 v99, 0xbfb8aa3b, v112
	v_mul_f32_e32 v102, 0xbfb8aa3b, v113
	v_exp_f32_e32 v99, v99
	v_exp_f32_e32 v102, v102
	v_pk_mul_f32 v[108:109], v[108:109], v[118:119] op_sel_hi:[1,0]
	v_add_f32_e32 v99, 1.0, v99
	v_add_f32_e32 v102, 1.0, v102
	v_rcp_f32_e32 v99, v99
	v_rcp_f32_e32 v102, v102
	v_mul_f32_e32 v99, v112, v99
	v_mul_f32_e32 v102, v113, v102
	v_mul_f32_e32 v99, v104, v99
	v_mul_f32_e32 v102, v105, v102
	v_cvt_pk_bf16_f32 v99, v99, v102
	v_mul_f32_e32 v102, 0xbfb8aa3b, v106
	v_exp_f32_e32 v102, v102
	s_nop 0
	v_add_f32_e32 v102, 1.0, v102
	v_rcp_f32_e32 v102, v102
	s_nop 0
	v_mul_f32_e32 v102, v106, v102
	v_mul_f32_e32 v100, v100, v102
	v_mul_f32_e32 v102, 0xbfb8aa3b, v107
	v_exp_f32_e32 v102, v102
	s_nop 0
	v_add_f32_e32 v102, 1.0, v102
	v_rcp_f32_e32 v102, v102
	s_nop 0
	v_mul_f32_e32 v102, v107, v102
	v_mul_f32_e32 v101, v101, v102
	v_cvt_pk_bf16_f32 v100, v100, v101
	v_mul_f32_e32 v101, 0xbfb8aa3b, v108
	v_mul_f32_e32 v102, 0xbfb8aa3b, v109
	v_exp_f32_e32 v101, v101
	v_exp_f32_e32 v102, v102
	v_add_f32_e32 v101, 1.0, v101
	v_add_f32_e32 v102, 1.0, v102
	v_rcp_f32_e32 v101, v101
	v_rcp_f32_e32 v102, v102
	v_mul_f32_e32 v101, v108, v101
	v_mul_f32_e32 v102, v109, v102
	v_mul_f32_e32 v101, v120, v101
	v_mul_f32_e32 v102, v121, v102
	v_cvt_pk_bf16_f32 v101, v101, v102
	v_mad_i64_i32 v[102:103], s[16:17], v119, s18, v[114:115]
	v_lshl_add_u64 v[102:103], v[102:103], 0, v[116:117]
	global_store_dwordx4 v[102:103], v[98:101], off
	s_nop 1
	v_pk_mul_f32 v[98:99], v[84:85], v[140:141] op_sel_hi:[1,0]
	v_pk_mul_f32 v[84:85], v[82:83], v[140:141] op_sel_hi:[1,0]
	v_mul_f32_e32 v82, 0xbfb8aa3b, v94
	v_mul_f32_e32 v83, 0xbfb8aa3b, v95
	v_exp_f32_e32 v82, v82
	v_exp_f32_e32 v83, v83
	v_or_b32_e32 v100, 32, v154
	v_add_f32_e32 v82, 1.0, v82
	v_add_f32_e32 v83, 1.0, v83
	v_rcp_f32_e32 v82, v82
	v_rcp_f32_e32 v83, v83
	v_mul_f32_e32 v82, v94, v82
	v_mul_f32_e32 v83, v95, v83
	v_mul_f32_e32 v82, v86, v82
	v_mul_f32_e32 v83, v87, v83
	v_cvt_pk_bf16_f32 v82, v82, v83
	v_mul_f32_e32 v83, 0xbfb8aa3b, v96
	v_mul_f32_e32 v86, 0xbfb8aa3b, v97
	v_exp_f32_e32 v83, v83
	v_exp_f32_e32 v86, v86
	v_add_f32_e32 v83, 1.0, v83
	v_add_f32_e32 v86, 1.0, v86
	v_rcp_f32_e32 v83, v83
	v_rcp_f32_e32 v86, v86
	v_mul_f32_e32 v83, v96, v83
	v_mul_f32_e32 v86, v97, v86
	v_mul_f32_e32 v83, v88, v83
	v_mul_f32_e32 v86, v89, v86
	v_cvt_pk_bf16_f32 v83, v83, v86
	v_mul_f32_e32 v86, 0xbfb8aa3b, v90
	v_exp_f32_e32 v86, v86
	s_nop 0
	v_add_f32_e32 v86, 1.0, v86
	v_rcp_f32_e32 v86, v86
	s_nop 0
	v_mul_f32_e32 v86, v90, v86
	v_mul_f32_e32 v84, v84, v86
	v_mul_f32_e32 v86, 0xbfb8aa3b, v91
	v_exp_f32_e32 v86, v86
	s_nop 0
	v_add_f32_e32 v86, 1.0, v86
	v_rcp_f32_e32 v86, v86
	s_nop 0
	v_mul_f32_e32 v86, v91, v86
	v_mul_f32_e32 v85, v85, v86
	v_cvt_pk_bf16_f32 v84, v84, v85
	v_mul_f32_e32 v85, 0xbfb8aa3b, v92
	v_mul_f32_e32 v86, 0xbfb8aa3b, v93
	v_exp_f32_e32 v85, v85
	v_exp_f32_e32 v86, v86
	v_add_f32_e32 v85, 1.0, v85
	v_add_f32_e32 v86, 1.0, v86
	v_rcp_f32_e32 v85, v85
	v_rcp_f32_e32 v86, v86
	v_mul_f32_e32 v85, v92, v85
	v_mul_f32_e32 v86, v93, v86
	v_mul_f32_e32 v85, v98, v85
	v_mul_f32_e32 v86, v99, v86
	v_cvt_pk_bf16_f32 v85, v85, v86
	v_mad_i64_i32 v[86:87], s[16:17], v100, s18, v[114:115]
	v_lshl_add_u64 v[86:87], v[86:87], 0, v[116:117]
	global_store_dwordx4 v[86:87], v[82:85], off
	s_nop 1
	v_or_b32_e32 v83, 48, v154
	v_mov_b32_e32 v82, v141
	v_pk_mul_f32 v[78:79], v[78:79], v[82:83] op_sel_hi:[1,0]
	v_pk_mul_f32 v[84:85], v[68:69], v[82:83] op_sel_hi:[1,0]
	v_pk_mul_f32 v[68:69], v[66:67], v[82:83] op_sel_hi:[1,0]
	v_mul_f32_e32 v66, 0xbfb8aa3b, v78
	v_mul_f32_e32 v67, 0xbfb8aa3b, v79
	v_exp_f32_e32 v66, v66
	v_exp_f32_e32 v67, v67
	v_pk_mul_f32 v[70:71], v[70:71], v[82:83] op_sel_hi:[1,0]
	v_pk_mul_f32 v[80:81], v[80:81], v[82:83] op_sel_hi:[1,0]
	v_add_f32_e32 v66, 1.0, v66
	v_add_f32_e32 v67, 1.0, v67
	v_rcp_f32_e32 v66, v66
	v_rcp_f32_e32 v67, v67
	v_pk_mul_f32 v[72:73], v[72:73], v[82:83] op_sel_hi:[1,0]
	v_pk_mul_f32 v[74:75], v[74:75], v[82:83] op_sel_hi:[1,0]
	v_mul_f32_e32 v66, v78, v66
	v_mul_f32_e32 v67, v79, v67
	v_mul_f32_e32 v66, v70, v66
	v_mul_f32_e32 v67, v71, v67
	v_cvt_pk_bf16_f32 v66, v66, v67
	v_mul_f32_e32 v67, 0xbfb8aa3b, v80
	v_mul_f32_e32 v70, 0xbfb8aa3b, v81
	v_exp_f32_e32 v67, v67
	v_exp_f32_e32 v70, v70
	v_pk_mul_f32 v[76:77], v[76:77], v[82:83] op_sel_hi:[1,0]
	v_add_f32_e32 v67, 1.0, v67
	v_add_f32_e32 v70, 1.0, v70
	v_rcp_f32_e32 v67, v67
	v_rcp_f32_e32 v70, v70
	v_mul_f32_e32 v67, v80, v67
	v_mul_f32_e32 v70, v81, v70
	v_mul_f32_e32 v67, v72, v67
	v_mul_f32_e32 v70, v73, v70
	v_cvt_pk_bf16_f32 v67, v67, v70
	v_mul_f32_e32 v70, 0xbfb8aa3b, v74
	v_exp_f32_e32 v70, v70
	s_nop 0
	v_add_f32_e32 v70, 1.0, v70
	v_rcp_f32_e32 v70, v70
	s_nop 0
	v_mul_f32_e32 v70, v74, v70
	v_mul_f32_e32 v68, v68, v70
	v_mul_f32_e32 v70, 0xbfb8aa3b, v75
	v_exp_f32_e32 v70, v70
	s_nop 0
	v_add_f32_e32 v70, 1.0, v70
	v_rcp_f32_e32 v70, v70
	s_nop 0
	v_mul_f32_e32 v70, v75, v70
	v_mul_f32_e32 v69, v69, v70
	v_cvt_pk_bf16_f32 v68, v68, v69
	v_mul_f32_e32 v69, 0xbfb8aa3b, v76
	v_mul_f32_e32 v70, 0xbfb8aa3b, v77
	v_exp_f32_e32 v69, v69
	v_exp_f32_e32 v70, v70
	v_add_f32_e32 v69, 1.0, v69
	v_add_f32_e32 v70, 1.0, v70
	v_rcp_f32_e32 v69, v69
	v_rcp_f32_e32 v70, v70
	v_mul_f32_e32 v69, v76, v69
	v_mul_f32_e32 v70, v77, v70
	v_mul_f32_e32 v69, v84, v69
	v_mul_f32_e32 v70, v85, v70
	v_cvt_pk_bf16_f32 v69, v69, v70
	v_mad_i64_i32 v[70:71], s[16:17], v83, s18, v[114:115]
	v_lshl_add_u64 v[70:71], v[70:71], 0, v[116:117]
	global_store_dwordx4 v[70:71], v[66:69], off
	s_nop 1
	v_pk_mul_f32 v[66:67], v[52:53], v[138:139] op_sel_hi:[1,0]
	v_pk_mul_f32 v[52:53], v[50:51], v[138:139] op_sel_hi:[1,0]
	v_mul_f32_e32 v50, 0xbfb8aa3b, v62
	v_mul_f32_e32 v51, 0xbfb8aa3b, v63
	v_exp_f32_e32 v50, v50
	v_exp_f32_e32 v51, v51
	v_add_u32_e32 v68, 0x80, v154
	v_add_f32_e32 v50, 1.0, v50
	v_add_f32_e32 v51, 1.0, v51
	v_rcp_f32_e32 v50, v50
	v_rcp_f32_e32 v51, v51
	v_mul_f32_e32 v50, v62, v50
	v_mul_f32_e32 v51, v63, v51
	v_mul_f32_e32 v50, v54, v50
	v_mul_f32_e32 v51, v55, v51
	v_cvt_pk_bf16_f32 v50, v50, v51
	v_mul_f32_e32 v51, 0xbfb8aa3b, v64
	v_mul_f32_e32 v54, 0xbfb8aa3b, v65
	v_exp_f32_e32 v51, v51
	v_exp_f32_e32 v54, v54
	v_add_f32_e32 v51, 1.0, v51
	v_add_f32_e32 v54, 1.0, v54
	v_rcp_f32_e32 v51, v51
	v_rcp_f32_e32 v54, v54
	v_mul_f32_e32 v51, v64, v51
	v_mul_f32_e32 v54, v65, v54
	v_mul_f32_e32 v51, v56, v51
	v_mul_f32_e32 v54, v57, v54
	v_cvt_pk_bf16_f32 v51, v51, v54
	v_mul_f32_e32 v54, 0xbfb8aa3b, v58
	v_exp_f32_e32 v54, v54
	s_nop 0
	v_add_f32_e32 v54, 1.0, v54
	v_rcp_f32_e32 v54, v54
	s_nop 0
	v_mul_f32_e32 v54, v58, v54
	v_mul_f32_e32 v52, v52, v54
	v_mul_f32_e32 v54, 0xbfb8aa3b, v59
	v_exp_f32_e32 v54, v54
	s_nop 0
	v_add_f32_e32 v54, 1.0, v54
	v_rcp_f32_e32 v54, v54
	s_nop 0
	v_mul_f32_e32 v54, v59, v54
	v_mul_f32_e32 v53, v53, v54
	v_cvt_pk_bf16_f32 v52, v52, v53
	v_mul_f32_e32 v53, 0xbfb8aa3b, v60
	v_mul_f32_e32 v54, 0xbfb8aa3b, v61
	v_exp_f32_e32 v53, v53
	v_exp_f32_e32 v54, v54
	v_add_f32_e32 v53, 1.0, v53
	v_add_f32_e32 v54, 1.0, v54
	v_rcp_f32_e32 v53, v53
	v_rcp_f32_e32 v54, v54
	v_mul_f32_e32 v53, v60, v53
	v_mul_f32_e32 v54, v61, v54
	v_mul_f32_e32 v53, v66, v53
	v_mul_f32_e32 v54, v67, v54
	v_cvt_pk_bf16_f32 v53, v53, v54
	v_mad_i64_i32 v[54:55], s[16:17], v68, s18, v[114:115]
	v_lshl_add_u64 v[54:55], v[54:55], 0, v[116:117]
	global_store_dwordx4 v[54:55], v[50:53], off
	s_nop 1
	v_add_u32_e32 v51, 0x90, v154
	v_mov_b32_e32 v50, v139
	v_pk_mul_f32 v[46:47], v[46:47], v[50:51] op_sel_hi:[1,0]
	v_pk_mul_f32 v[52:53], v[36:37], v[50:51] op_sel_hi:[1,0]
	v_pk_mul_f32 v[36:37], v[34:35], v[50:51] op_sel_hi:[1,0]
	v_mul_f32_e32 v34, 0xbfb8aa3b, v46
	v_mul_f32_e32 v35, 0xbfb8aa3b, v47
	v_exp_f32_e32 v34, v34
	v_exp_f32_e32 v35, v35
	v_pk_mul_f32 v[38:39], v[38:39], v[50:51] op_sel_hi:[1,0]
	v_pk_mul_f32 v[48:49], v[48:49], v[50:51] op_sel_hi:[1,0]
	v_add_f32_e32 v34, 1.0, v34
	v_add_f32_e32 v35, 1.0, v35
	v_rcp_f32_e32 v34, v34
	v_rcp_f32_e32 v35, v35
	v_pk_mul_f32 v[40:41], v[40:41], v[50:51] op_sel_hi:[1,0]
	v_pk_mul_f32 v[42:43], v[42:43], v[50:51] op_sel_hi:[1,0]
	v_mul_f32_e32 v34, v46, v34
	v_mul_f32_e32 v35, v47, v35
	v_mul_f32_e32 v34, v38, v34
	v_mul_f32_e32 v35, v39, v35
	v_cvt_pk_bf16_f32 v34, v34, v35
	v_mul_f32_e32 v35, 0xbfb8aa3b, v48
	v_mul_f32_e32 v38, 0xbfb8aa3b, v49
	v_exp_f32_e32 v35, v35
	v_exp_f32_e32 v38, v38
	v_pk_mul_f32 v[44:45], v[44:45], v[50:51] op_sel_hi:[1,0]
	v_add_f32_e32 v35, 1.0, v35
	v_add_f32_e32 v38, 1.0, v38
	v_rcp_f32_e32 v35, v35
	v_rcp_f32_e32 v38, v38
	v_mul_f32_e32 v35, v48, v35
	v_mul_f32_e32 v38, v49, v38
	v_mul_f32_e32 v35, v40, v35
	v_mul_f32_e32 v38, v41, v38
	v_cvt_pk_bf16_f32 v35, v35, v38
	v_mul_f32_e32 v38, 0xbfb8aa3b, v42
	v_exp_f32_e32 v38, v38
	s_nop 0
	v_add_f32_e32 v38, 1.0, v38
	v_rcp_f32_e32 v38, v38
	s_nop 0
	v_mul_f32_e32 v38, v42, v38
	v_mul_f32_e32 v36, v36, v38
	v_mul_f32_e32 v38, 0xbfb8aa3b, v43
	v_exp_f32_e32 v38, v38
	s_nop 0
	v_add_f32_e32 v38, 1.0, v38
	v_rcp_f32_e32 v38, v38
	s_nop 0
	v_mul_f32_e32 v38, v43, v38
	v_mul_f32_e32 v37, v37, v38
	v_cvt_pk_bf16_f32 v36, v36, v37
	v_mul_f32_e32 v37, 0xbfb8aa3b, v44
	v_mul_f32_e32 v38, 0xbfb8aa3b, v45
	v_exp_f32_e32 v37, v37
	v_exp_f32_e32 v38, v38
	v_add_f32_e32 v37, 1.0, v37
	v_add_f32_e32 v38, 1.0, v38
	v_rcp_f32_e32 v37, v37
	v_rcp_f32_e32 v38, v38
	v_mul_f32_e32 v37, v44, v37
	v_mul_f32_e32 v38, v45, v38
	v_mul_f32_e32 v37, v52, v37
	v_mul_f32_e32 v38, v53, v38
	v_cvt_pk_bf16_f32 v37, v37, v38
	v_mad_i64_i32 v[38:39], s[16:17], v51, s18, v[114:115]
	v_lshl_add_u64 v[38:39], v[38:39], 0, v[116:117]
	global_store_dwordx4 v[38:39], v[34:37], off
	s_nop 1
	v_pk_mul_f32 v[34:35], v[20:21], v[136:137] op_sel_hi:[1,0]
	v_pk_mul_f32 v[20:21], v[18:19], v[136:137] op_sel_hi:[1,0]
	v_mul_f32_e32 v18, 0xbfb8aa3b, v30
	v_mul_f32_e32 v19, 0xbfb8aa3b, v31
	v_exp_f32_e32 v18, v18
	v_exp_f32_e32 v19, v19
	v_add_u32_e32 v36, 0xa0, v154
	v_add_f32_e32 v18, 1.0, v18
	v_add_f32_e32 v19, 1.0, v19
	v_rcp_f32_e32 v18, v18
	v_rcp_f32_e32 v19, v19
	v_mul_f32_e32 v18, v30, v18
	v_mul_f32_e32 v19, v31, v19
	v_mul_f32_e32 v18, v22, v18
	v_mul_f32_e32 v19, v23, v19
	v_cvt_pk_bf16_f32 v18, v18, v19
	v_mul_f32_e32 v19, 0xbfb8aa3b, v32
	v_mul_f32_e32 v22, 0xbfb8aa3b, v33
	v_exp_f32_e32 v19, v19
	v_exp_f32_e32 v22, v22
	v_add_f32_e32 v19, 1.0, v19
	v_add_f32_e32 v22, 1.0, v22
	v_rcp_f32_e32 v19, v19
	v_rcp_f32_e32 v22, v22
	v_mul_f32_e32 v19, v32, v19
	v_mul_f32_e32 v22, v33, v22
	v_mul_f32_e32 v19, v24, v19
	v_mul_f32_e32 v22, v25, v22
	v_cvt_pk_bf16_f32 v19, v19, v22
	v_mul_f32_e32 v22, 0xbfb8aa3b, v26
	v_exp_f32_e32 v22, v22
	s_nop 0
	v_add_f32_e32 v22, 1.0, v22
	v_rcp_f32_e32 v22, v22
	s_nop 0
	v_mul_f32_e32 v22, v26, v22
	v_mul_f32_e32 v20, v20, v22
	v_mul_f32_e32 v22, 0xbfb8aa3b, v27
	v_exp_f32_e32 v22, v22
	s_nop 0
	v_add_f32_e32 v22, 1.0, v22
	v_rcp_f32_e32 v22, v22
	s_nop 0
	v_mul_f32_e32 v22, v27, v22
	v_mul_f32_e32 v21, v21, v22
	v_cvt_pk_bf16_f32 v20, v20, v21
	v_mul_f32_e32 v21, 0xbfb8aa3b, v28
	v_mul_f32_e32 v22, 0xbfb8aa3b, v29
	v_exp_f32_e32 v21, v21
	v_exp_f32_e32 v22, v22
	v_add_f32_e32 v21, 1.0, v21
	v_add_f32_e32 v22, 1.0, v22
	v_rcp_f32_e32 v21, v21
	v_rcp_f32_e32 v22, v22
	v_mul_f32_e32 v21, v28, v21
	v_mul_f32_e32 v22, v29, v22
	v_mul_f32_e32 v21, v34, v21
	v_mul_f32_e32 v22, v35, v22
	v_cvt_pk_bf16_f32 v21, v21, v22
	v_mad_i64_i32 v[22:23], s[16:17], v36, s18, v[114:115]
	v_lshl_add_u64 v[22:23], v[22:23], 0, v[116:117]
	global_store_dwordx4 v[22:23], v[18:21], off
	s_nop 1
	v_add_u32_e32 v19, 0xb0, v154
	v_mov_b32_e32 v18, v137
	v_pk_mul_f32 v[14:15], v[14:15], v[18:19] op_sel_hi:[1,0]
	v_pk_mul_f32 v[20:21], v[4:5], v[18:19] op_sel_hi:[1,0]
	v_pk_mul_f32 v[4:5], v[2:3], v[18:19] op_sel_hi:[1,0]
	v_mul_f32_e32 v2, 0xbfb8aa3b, v14
	v_mul_f32_e32 v3, 0xbfb8aa3b, v15
	v_exp_f32_e32 v2, v2
	v_exp_f32_e32 v3, v3
	v_pk_mul_f32 v[6:7], v[6:7], v[18:19] op_sel_hi:[1,0]
	v_pk_mul_f32 v[16:17], v[16:17], v[18:19] op_sel_hi:[1,0]
	v_add_f32_e32 v2, 1.0, v2
	v_add_f32_e32 v3, 1.0, v3
	v_rcp_f32_e32 v2, v2
	v_rcp_f32_e32 v3, v3
	v_pk_mul_f32 v[8:9], v[8:9], v[18:19] op_sel_hi:[1,0]
	v_pk_mul_f32 v[10:11], v[10:11], v[18:19] op_sel_hi:[1,0]
	v_mul_f32_e32 v2, v14, v2
	v_mul_f32_e32 v3, v15, v3
	v_mul_f32_e32 v2, v6, v2
	v_mul_f32_e32 v3, v7, v3
	v_cvt_pk_bf16_f32 v2, v2, v3
	v_mul_f32_e32 v3, 0xbfb8aa3b, v16
	v_mul_f32_e32 v6, 0xbfb8aa3b, v17
	v_exp_f32_e32 v3, v3
	v_exp_f32_e32 v6, v6
	v_pk_mul_f32 v[12:13], v[12:13], v[18:19] op_sel_hi:[1,0]
	v_add_f32_e32 v3, 1.0, v3
	v_add_f32_e32 v6, 1.0, v6
	v_rcp_f32_e32 v3, v3
	v_rcp_f32_e32 v6, v6
	v_mul_f32_e32 v3, v16, v3
	v_mul_f32_e32 v6, v17, v6
	v_mul_f32_e32 v3, v8, v3
	v_mul_f32_e32 v6, v9, v6
	v_cvt_pk_bf16_f32 v3, v3, v6
	v_mul_f32_e32 v6, 0xbfb8aa3b, v10
	v_exp_f32_e32 v6, v6
	s_nop 0
	v_add_f32_e32 v6, 1.0, v6
	v_rcp_f32_e32 v6, v6
	s_nop 0
	v_mul_f32_e32 v6, v10, v6
	v_mul_f32_e32 v4, v4, v6
	v_mul_f32_e32 v6, 0xbfb8aa3b, v11
	v_exp_f32_e32 v6, v6
	s_nop 0
	v_add_f32_e32 v6, 1.0, v6
	v_rcp_f32_e32 v6, v6
	s_nop 0
	v_mul_f32_e32 v6, v11, v6
	v_mul_f32_e32 v5, v5, v6
	v_cvt_pk_bf16_f32 v4, v4, v5
	v_mul_f32_e32 v5, 0xbfb8aa3b, v12
	v_mul_f32_e32 v6, 0xbfb8aa3b, v13
	v_exp_f32_e32 v5, v5
	v_exp_f32_e32 v6, v6
	v_add_f32_e32 v5, 1.0, v5
	v_add_f32_e32 v6, 1.0, v6
	v_rcp_f32_e32 v5, v5
	v_rcp_f32_e32 v6, v6
	v_mul_f32_e32 v5, v12, v5
	v_mul_f32_e32 v6, v13, v6
	v_mul_f32_e32 v5, v20, v5
	v_mul_f32_e32 v6, v21, v6
	v_cvt_pk_bf16_f32 v5, v5, v6
	v_mad_i64_i32 v[6:7], s[16:17], v19, s18, v[114:115]
	v_lshl_add_u64 v[6:7], v[6:7], 0, v[116:117]
	global_store_dwordx4 v[6:7], v[2:5], off
	s_andn2_b64 vcc, exec, s[10:11]
	s_mov_b64 s[10:11], -1
	s_cbranch_vccnz .LBB0_684
	s_and_saveexec_b64 s[10:11], s[40:41]
	s_waitcnt vmcnt(8)
	v_add_f32_e32 v136, v168, v169
	v_add_f32_e32 v137, v170, v171
	v_add_f32_e32 v136, v136, v137
	v_add_f32_e32 v137, v164, v165
	v_add_f32_e32 v138, v166, v167
	v_add_f32_e32 v137, v137, v138
	v_add_f32_e32 v136, v136, v137
	v_add_f32_e32 v137, v160, v161
	v_add_f32_e32 v138, v162, v163
	v_add_f32_e32 v137, v137, v138
	v_add_f32_e32 v136, v136, v137
	v_add_f32_e32 v137, v172, v173
	v_add_f32_e32 v138, v174, v175
	v_add_f32_e32 v137, v137, v138
	v_add_f32_e32 v136, v136, v137
	s_mov_b32 s16, 0x800000
	v_fmamk_f32 v136, v136, 0x3a800000, v241
	v_mul_f32_e32 v137, 0x4b800000, v136
	v_cmp_gt_f32_e32 vcc, s16, v136
	s_nop 1
	v_cndmask_b32_e32 v136, v136, v137, vcc
	v_rsq_f32_e32 v136, v136
	s_nop 0
	v_mul_f32_e32 v137, 0x45800000, v136
	v_cndmask_b32_e32 v153, v136, v137, vcc
	s_lshl_b32 s16, s33, 8
	s_xor_b32 s16, s16, 0x100
	v_lshl_add_u32 v2, s16, 2, v149
	ds_write_b32 v2, v153
	s_or_b64 exec, exec, s[10:11]
	s_andn2_b64 vcc, exec, s[4:5]
	s_cbranch_vccnz .LBB0_683
	s_barrier
	s_branch .LBB0_683
	s_nop 0
	s_nop 0
